# P0 split: only layer-0 + first GLA-in weights transposed up front (hand-written LDS-DMA loop); the rest converted by the 128 idle workgroups of layer 1's GLA scan
# speedup vs baseline: 1.0112x; 1.0064x over previous
; __device__ __forceinline__ void p0_prologue(KP P, LAS unsigned char* lds, int G) {
;     ...
;     const int gw = blockIdx.x * NWAVES + wid, NGW = G * NWAVES;
;     constexpr int I_AIN = 16 * 96, I_AO = 16 * 32, I_GIN = 16 * 96, I_GO = 16 * 32, I_UP = 16 * 128, I_DN = 64 * 32;
;     constexpr int NITEMS = 2 * I_AIN + 2 * I_AO + 2 * I_GIN + 2 * I_GO + 4 * I_UP + 4 * I_DN;
;     for (int it = gw; it < NITEMS; it += NGW) {
;         int r = it;
;         if (r < 2 * I_AIN) { const int j = r / I_AIN; r -= j * I_AIN; const int kb = r / 96, nb = r % 96;
;             p0_transpose_item(P->attn_w_in + (size_t)j * 1024 * 3072, 3072, 1024, (bf16_t*)(P->ws + WS_WQKV + j * WS_WQKV_STRIDE), 64 * kb, 32 * nb, 32 * nb, scr, lane); continue; }
;         r -= 2 * I_AIN;
;         if (r < 2 * I_AO) { const int j = r / I_AO; r -= j * I_AO; const int kb = r / 32, nb = r % 32;
;             p0_transpose_item(P->attn_w_out + (size_t)j * 1024 * 1024, 1024, 1024, (bf16_t*)(P->ws + WS_WAO + j * WS_WAO_STRIDE), 64 * kb, 32 * nb, 32 * nb, scr, lane); continue; }
;         r -= 2 * I_AO;
;         if (r < 2 * I_GIN) { const int j = r / I_GIN; r -= j * I_GIN; const int kb = r / 96, nb = r % 96; const int n0 = 32 * nb;
;             const int orow = n0 < 1024 ? n0 : (n0 < 2048 ? n0 + 1024 : n0 - 1024);
;             p0_transpose_item(P->gla_w_in + (size_t)j * 1024 * 3088, 3088, 1024, (bf16_t*)(P->ws + WS_WGLA + j * WS_WGLA_STRIDE), 64 * kb, n0, orow, scr, lane); continue; }
;         r -= 2 * I_GIN;
;         if (r < 2 * I_GO) { const int j = r / I_GO; r -= j * I_GO; const int kb = r / 32, nb = r % 32;
;             p0_transpose_item(P->gla_w_out + (size_t)j * 1024 * 1024, 1024, 1024, (bf16_t*)(P->ws + WS_WGO + j * WS_WGO_STRIDE), 64 * kb, 32 * nb, 32 * nb, scr, lane); continue; }
;         r -= 2 * I_GO;
;         if (r < 4 * I_UP) { const int j = r / I_UP; r -= j * I_UP; const int kb = r / 128, nb = r % 128;
;             p0_transpose_item(P->mlp_up + (size_t)j * 1024 * 4096, 4096, 1024, (bf16_t*)(P->ws + WS_WUP + j * WS_WUP_STRIDE), 64 * kb, 32 * nb, 32 * nb, scr, lane); continue; }
;         r -= 4 * I_UP;
;         { const int j = r / I_DN; r -= j * I_DN; const int kb = r / 32, nb = r % 32;
;             p0_transpose_item(P->mlp_dn + (size_t)j * 4096 * 1024, 1024, 4096, (bf16_t*)(P->ws + WS_WDN + j * WS_WDN_STRIDE), 64 * kb, 32 * nb, 32 * nb, scr, lane); }
.LBB0_5:
	s_or_b64 exec, exec, s[0:1]
	s_mov_b64 s[0:1], s[90:91]
	v_mov_b32_e32 v3, v194
	s_lshl_b32 s88, s94, 3
	v_readfirstlane_b32 s2, v3
	s_ashr_i32 s3, s2, 6
	s_lshl_b32 s2, s92, 3
	v_writelane_b32 v253, s2, 4
	s_add_i32 s2, s3, s2
	s_cmpk_gt_i32 s2, 0x5fff
	s_cbranch_scc1 .LBB0_40
	v_and_b32_e32 v54, 63, v3
	s_mul_i32 s4, s3, 0x4400
	s_load_dwordx2 s[30:31], s[0:1], 0x18
	s_load_dwordx2 s[32:33], s[0:1], 0x30
	s_load_dwordx2 s[34:35], s[0:1], 0x38
	s_load_dwordx2 s[38:39], s[0:1], 0x68
	s_load_dwordx2 s[40:41], s[0:1], 0x70
	s_load_dwordx2 s[42:43], s[0:1], 0x88
	v_and_b32_e32 v55, 7, v54
	v_lshrrev_b32_e32 v56, 3, v54
	v_mul_u32_u24_e32 v57, 0x410, v55
	v_lshlrev_b32_e32 v58, 4, v55
	v_lshl_add_u32 v57, v56, 2, v57
	v_add_u32_e32 v57, s4, v57
	v_add_u32_e32 v61, 0x2080, v57
	s_mov_b32 s44, 0
	s_waitcnt lgkmcnt(0)
	s_cmp_lt_u32 s2, 7680
	s_cbranch_scc0 .LBB0_40
	s_mov_b32 s6, s2
	s_cmp_lt_u32 s6, 1536
	s_cbranch_scc0 .Lp0a_da0_1
	s_mul_i32 s20, s6, 683
	s_lshr_b32 s20, s20, 16
	s_mul_i32 s21, s20, 96
	s_sub_u32 s21, s6, s21
	s_lshl_b32 s20, s20, 6
	s_lshl_b32 s21, s21, 5
	s_mul_i32 s23, s20, 3072
	s_add_u32 s23, s23, s21
	s_lshl_b32 s23, s23, 2
	s_add_u32 s8, s30, s23
	s_addc_u32 s9, s31, 0
	s_mov_b32 s10, 12288
	s_mul_i32 s22, s21, 1024
	s_add_u32 s22, s22, s20
	s_lshl_b32 s22, s22, 1
	s_add_u32 s22, s22, 0x100000
	s_add_u32 s12, s42, s22
	s_addc_u32 s13, s43, 0
	s_mov_b32 s14, 2048
	s_branch .Lp0a_da0_done
.Lp0a_da0_1:
	s_sub_u32 s6, s6, 1536
	s_cmp_lt_u32 s6, 512
	s_cbranch_scc0 .Lp0a_da0_2
	s_lshr_b32 s20, s6, 5
	s_and_b32 s21, s6, 31
	s_lshl_b32 s20, s20, 6
	s_lshl_b32 s21, s21, 5
	s_mul_i32 s23, s20, 1024
	s_add_u32 s23, s23, s21
	s_lshl_b32 s23, s23, 2
	s_add_u32 s8, s32, s23
	s_addc_u32 s9, s33, 0
	s_mov_b32 s10, 4096
	s_mul_i32 s22, s21, 1024
	s_add_u32 s22, s22, s20
	s_lshl_b32 s22, s22, 1
	s_add_u32 s22, s22, 0xd00000
	s_add_u32 s12, s42, s22
	s_addc_u32 s13, s43, 0
	s_mov_b32 s14, 2048
	s_branch .Lp0a_da0_done
.Lp0a_da0_2:
	s_sub_u32 s6, s6, 512
	s_cmp_lt_u32 s6, 1536
	s_cbranch_scc0 .Lp0a_da0_3
	s_mul_i32 s20, s6, 683
	s_lshr_b32 s20, s20, 16
	s_mul_i32 s21, s20, 96
	s_sub_u32 s21, s6, s21
	s_lshl_b32 s20, s20, 6
	s_lshl_b32 s21, s21, 5
	s_mul_i32 s23, s20, 3088
	s_add_u32 s23, s23, s21
	s_lshl_b32 s23, s23, 2
	s_add_u32 s8, s34, s23
	s_addc_u32 s9, s35, 0
	s_mov_b32 s10, 12352
	s_add_u32 s22, s21, 0x400
	s_sub_u32 s23, s21, 0x400
	s_cmp_lt_u32 s21, 0x800
	s_cselect_b32 s22, s22, s23
	s_cmp_lt_u32 s21, 0x400
	s_cselect_b32 s21, s21, s22
	s_mul_i32 s22, s21, 1024
	s_add_u32 s22, s22, s20
	s_lshl_b32 s22, s22, 1
	s_add_u32 s22, s22, 0x1100000
	s_add_u32 s12, s42, s22
	s_addc_u32 s13, s43, 0
	s_mov_b32 s14, 2048
	s_branch .Lp0a_da0_done
.Lp0a_da0_3:
	s_sub_u32 s6, s6, 1536
	s_cmp_lt_u32 s6, 2048
	s_cbranch_scc0 .Lp0a_da0_4
	s_lshr_b32 s20, s6, 7
	s_and_b32 s21, s6, 127
	s_lshl_b32 s20, s20, 6
	s_lshl_b32 s21, s21, 5
	s_mul_i32 s23, s20, 4096
	s_add_u32 s23, s23, s21
	s_lshl_b32 s23, s23, 2
	s_add_u32 s8, s38, s23
	s_addc_u32 s9, s39, 0
	s_mov_b32 s10, 16384
	s_mul_i32 s22, s21, 1024
	s_add_u32 s22, s22, s20
	s_lshl_b32 s22, s22, 1
	s_add_u32 s22, s22, 0x2300000
	s_add_u32 s12, s42, s22
	s_addc_u32 s13, s43, 0
	s_mov_b32 s14, 2048
	s_branch .Lp0a_da0_done
.Lp0a_da0_4:
	s_sub_u32 s6, s6, 2048
	s_lshr_b32 s20, s6, 5
	s_and_b32 s21, s6, 31
	s_lshl_b32 s20, s20, 6
	s_lshl_b32 s21, s21, 5
	s_mul_i32 s23, s20, 1024
	s_add_u32 s23, s23, s21
	s_lshl_b32 s23, s23, 2
	s_add_u32 s8, s40, s23
	s_addc_u32 s9, s41, 0
	s_mov_b32 s10, 4096
	s_mul_i32 s22, s21, 4096
	s_add_u32 s22, s22, s20
	s_lshl_b32 s22, s22, 1
	s_add_u32 s22, s22, 0x4300000
	s_add_u32 s12, s42, s22
	s_addc_u32 s13, s43, 0
	s_mov_b32 s14, 8192

; __device__ __forceinline__ void p0_prologue(KP P, LAS unsigned char* lds, int G) {
;     ...
;     for (int it = gw; it < NITEMS; it += NGW) {
;         int r = it;
;         if (r < 2 * I_AIN) { const int j = r / I_AIN; r -= j * I_AIN; const int kb = r / 96, nb = r % 96;
;             p0_transpose_item(P->attn_w_in + (size_t)j * 1024 * 3072, 3072, 1024, (bf16_t*)(P->ws + WS_WQKV + j * WS_WQKV_STRIDE), 64 * kb, 32 * nb, 32 * nb, scr, lane); continue; }
;         r -= 2 * I_AIN;
;         if (r < 2 * I_AO) { const int j = r / I_AO; r -= j * I_AO; const int kb = r / 32, nb = r % 32;
;             p0_transpose_item(P->attn_w_out + (size_t)j * 1024 * 1024, 1024, 1024, (bf16_t*)(P->ws + WS_WAO + j * WS_WAO_STRIDE), 64 * kb, 32 * nb, 32 * nb, scr, lane); continue; }
;         r -= 2 * I_AO;
;         if (r < 2 * I_GIN) { const int j = r / I_GIN; r -= j * I_GIN; const int kb = r / 96, nb = r % 96; const int n0 = 32 * nb;
;             const int orow = n0 < 1024 ? n0 : (n0 < 2048 ? n0 + 1024 : n0 - 1024);
;             p0_transpose_item(P->gla_w_in + (size_t)j * 1024 * 3088, 3088, 1024, (bf16_t*)(P->ws + WS_WGLA + j * WS_WGLA_STRIDE), 64 * kb, n0, orow, scr, lane); continue; }
;         r -= 2 * I_GIN;
;         if (r < 2 * I_GO) { const int j = r / I_GO; r -= j * I_GO; const int kb = r / 32, nb = r % 32;
;             p0_transpose_item(P->gla_w_out + (size_t)j * 1024 * 1024, 1024, 1024, (bf16_t*)(P->ws + WS_WGO + j * WS_WGO_STRIDE), 64 * kb, 32 * nb, 32 * nb, scr, lane); continue; }
;         r -= 2 * I_GO;
;         if (r < 4 * I_UP) { const int j = r / I_UP; r -= j * I_UP; const int kb = r / 128, nb = r % 128;
;             p0_transpose_item(P->mlp_up + (size_t)j * 1024 * 4096, 4096, 1024, (bf16_t*)(P->ws + WS_WUP + j * WS_WUP_STRIDE), 64 * kb, 32 * nb, 32 * nb, scr, lane); continue; }
;         r -= 4 * I_UP;
;         { const int j = r / I_DN; r -= j * I_DN; const int kb = r / 32, nb = r % 32;
;             p0_transpose_item(P->mlp_dn + (size_t)j * 4096 * 1024, 1024, 4096, (bf16_t*)(P->ws + WS_WDN + j * WS_WDN_STRIDE), 64 * kb, 32 * nb, 32 * nb, scr, lane); }
.Lp0a_loop:
	s_cmp_lt_u32 s2, 7680
	s_cbranch_scc0 .Lp0a_lastA
	s_mov_b32 s6, s2
	s_cmp_lt_u32 s6, 1536
	s_cbranch_scc0 .Lp0a_db_1
	s_mul_i32 s20, s6, 683
	s_lshr_b32 s20, s20, 16
	s_mul_i32 s21, s20, 96
	s_sub_u32 s21, s6, s21
	s_lshl_b32 s20, s20, 6
	s_lshl_b32 s21, s21, 5
	s_mul_i32 s23, s20, 3072
	s_add_u32 s23, s23, s21
	s_lshl_b32 s23, s23, 2
	s_add_u32 s8, s30, s23
	s_addc_u32 s9, s31, 0
	s_mov_b32 s10, 12288
	s_mul_i32 s22, s21, 1024
	s_add_u32 s22, s22, s20
	s_lshl_b32 s22, s22, 1
	s_add_u32 s22, s22, 0x100000
	s_add_u32 s16, s42, s22
	s_addc_u32 s17, s43, 0
	s_mov_b32 s18, 2048
	s_branch .Lp0a_db_done
.Lp0a_db_1:
	s_sub_u32 s6, s6, 1536
	s_cmp_lt_u32 s6, 512
	s_cbranch_scc0 .Lp0a_db_2
	s_lshr_b32 s20, s6, 5
	s_and_b32 s21, s6, 31
	s_lshl_b32 s20, s20, 6
	s_lshl_b32 s21, s21, 5
	s_mul_i32 s23, s20, 1024
	s_add_u32 s23, s23, s21
	s_lshl_b32 s23, s23, 2
	s_add_u32 s8, s32, s23
	s_addc_u32 s9, s33, 0
	s_mov_b32 s10, 4096
	s_mul_i32 s22, s21, 1024
	s_add_u32 s22, s22, s20
	s_lshl_b32 s22, s22, 1
	s_add_u32 s22, s22, 0xd00000
	s_add_u32 s16, s42, s22
	s_addc_u32 s17, s43, 0
	s_mov_b32 s18, 2048
	s_branch .Lp0a_db_done
.Lp0a_db_2:
	s_sub_u32 s6, s6, 512
	s_cmp_lt_u32 s6, 1536
	s_cbranch_scc0 .Lp0a_db_3
	s_mul_i32 s20, s6, 683
	s_lshr_b32 s20, s20, 16
	s_mul_i32 s21, s20, 96
	s_sub_u32 s21, s6, s21
	s_lshl_b32 s20, s20, 6
	s_lshl_b32 s21, s21, 5
	s_mul_i32 s23, s20, 3088
	s_add_u32 s23, s23, s21
	s_lshl_b32 s23, s23, 2
	s_add_u32 s8, s34, s23
	s_addc_u32 s9, s35, 0
	s_mov_b32 s10, 12352
	s_add_u32 s22, s21, 0x400
	s_sub_u32 s23, s21, 0x400
	s_cmp_lt_u32 s21, 0x800
	s_cselect_b32 s22, s22, s23
	s_cmp_lt_u32 s21, 0x400
	s_cselect_b32 s21, s21, s22
	s_mul_i32 s22, s21, 1024
	s_add_u32 s22, s22, s20
	s_lshl_b32 s22, s22, 1
	s_add_u32 s22, s22, 0x1100000
	s_add_u32 s16, s42, s22
	s_addc_u32 s17, s43, 0
	s_mov_b32 s18, 2048
	s_branch .Lp0a_db_done
.Lp0a_db_3:
	s_sub_u32 s6, s6, 1536
	s_cmp_lt_u32 s6, 2048
	s_cbranch_scc0 .Lp0a_db_4
	s_lshr_b32 s20, s6, 7
	s_and_b32 s21, s6, 127
	s_lshl_b32 s20, s20, 6
	s_lshl_b32 s21, s21, 5
	s_mul_i32 s23, s20, 4096
	s_add_u32 s23, s23, s21
	s_lshl_b32 s23, s23, 2
	s_add_u32 s8, s38, s23
	s_addc_u32 s9, s39, 0
	s_mov_b32 s10, 16384
	s_mul_i32 s22, s21, 1024
	s_add_u32 s22, s22, s20
	s_lshl_b32 s22, s22, 1
	s_add_u32 s22, s22, 0x2300000
	s_add_u32 s16, s42, s22
	s_addc_u32 s17, s43, 0
	s_mov_b32 s18, 2048
	s_branch .Lp0a_db_done
.Lp0a_db_4:
	s_sub_u32 s6, s6, 2048
	s_lshr_b32 s20, s6, 5
	s_and_b32 s21, s6, 31
	s_lshl_b32 s20, s20, 6
	s_lshl_b32 s21, s21, 5
	s_mul_i32 s23, s20, 1024
	s_add_u32 s23, s23, s21
	s_lshl_b32 s23, s23, 2
	s_add_u32 s8, s40, s23
	s_addc_u32 s9, s41, 0
	s_mov_b32 s10, 4096
	s_mul_i32 s22, s21, 4096
	s_add_u32 s22, s22, s20
	s_lshl_b32 s22, s22, 1
	s_add_u32 s22, s22, 0x4300000
	s_add_u32 s16, s42, s22
	s_addc_u32 s17, s43, 0
	s_mov_b32 s18, 8192

; #define LAS __attribute__((address_space(3)))
; __device__ __forceinline__ unsigned pk_bf16(float lo, float hi) { f32x2_t v = {lo, hi}; bf16x2_t b = __builtin_convertvector(v, bf16x2_t); return __builtin_bit_cast(unsigned, b); }
; __device__ __forceinline__ void p0_transpose_item(const float* W, int ldw, int K, bf16_t* WT, int k0, int n0, int orow0, LAS float* scr, int lane) {
;     ...
;     const int c = lane & 7;
; #pragma unroll
;     for (int j = 0; j < 4; ++j) { const int n = (lane >> 3) + 8 * j; const LAS float* s = scr + (8 * c) * 33 + n;
;         u32x4 o; o.x = pk_bf16(s[0 * 33], s[1 * 33]); o.y = pk_bf16(s[2 * 33], s[3 * 33]); o.z = pk_bf16(s[4 * 33], s[5 * 33]); o.w = pk_bf16(s[6 * 33], s[7 * 33]);
;         *(u32x4*)(WT + (size_t)(orow0 + n) * K + k0 + 8 * c) = o; }
;     asm volatile("s_waitcnt lgkmcnt(0)" ::: "memory");
; __device__ __forceinline__ void p0_prologue(KP P, LAS unsigned char* lds, int G) {
;     ...
;     for (int it = gw; it < NITEMS; it += NGW) {
;         int r = it;
;         if (r < 2 * I_AIN) { const int j = r / I_AIN; r -= j * I_AIN; const int kb = r / 96, nb = r % 96;
;             p0_transpose_item(P->attn_w_in + (size_t)j * 1024 * 3072, 3072, 1024, (bf16_t*)(P->ws + WS_WQKV + j * WS_WQKV_STRIDE), 64 * kb, 32 * nb, 32 * nb, scr, lane); continue; }
.Lp0a_consA:
	ds_read2_b32 v[64:65], v57 offset0:0 offset1:32
	ds_read2_b32 v[66:67], v57 offset0:64 offset1:96
	ds_read2_b32 v[68:69], v57 offset0:128 offset1:160
	ds_read2_b32 v[70:71], v57 offset0:192 offset1:224
	ds_read2_b32 v[72:73], v57 offset0:8 offset1:40
	ds_read2_b32 v[74:75], v57 offset0:72 offset1:104
	ds_read2_b32 v[76:77], v57 offset0:136 offset1:168
	ds_read2_b32 v[78:79], v57 offset0:200 offset1:232
	ds_read2_b32 v[80:81], v57 offset0:16 offset1:48
	ds_read2_b32 v[82:83], v57 offset0:80 offset1:112
	ds_read2_b32 v[84:85], v57 offset0:144 offset1:176
	ds_read2_b32 v[86:87], v57 offset0:208 offset1:240
	ds_read2_b32 v[88:89], v57 offset0:24 offset1:56
	ds_read2_b32 v[90:91], v57 offset0:88 offset1:120
	ds_read2_b32 v[92:93], v57 offset0:152 offset1:184
	ds_read2_b32 v[94:95], v57 offset0:216 offset1:248
	s_waitcnt lgkmcnt(0)
	v_mad_u32_u24 v59, v56, s14, v58
	s_lshl_b32 s6, s14, 3
	v_cvt_pk_bf16_f32 v96, v64, v65
	v_cvt_pk_bf16_f32 v97, v66, v67
	v_cvt_pk_bf16_f32 v98, v68, v69
	v_cvt_pk_bf16_f32 v99, v70, v71
	global_store_dwordx4 v59, v[96:99], s[12:13]
	s_add_u32 s12, s12, s6
	s_addc_u32 s13, s13, 0
	s_nop 0
	v_cvt_pk_bf16_f32 v96, v72, v73
	v_cvt_pk_bf16_f32 v97, v74, v75
	v_cvt_pk_bf16_f32 v98, v76, v77
	v_cvt_pk_bf16_f32 v99, v78, v79
	global_store_dwordx4 v59, v[96:99], s[12:13]
	s_add_u32 s12, s12, s6
	s_addc_u32 s13, s13, 0
	s_nop 0
	v_cvt_pk_bf16_f32 v96, v80, v81
	v_cvt_pk_bf16_f32 v97, v82, v83
	v_cvt_pk_bf16_f32 v98, v84, v85
	v_cvt_pk_bf16_f32 v99, v86, v87
	global_store_dwordx4 v59, v[96:99], s[12:13]
	s_add_u32 s12, s12, s6
	s_addc_u32 s13, s13, 0
	s_nop 0
	v_cvt_pk_bf16_f32 v96, v88, v89
	v_cvt_pk_bf16_f32 v97, v90, v91
	v_cvt_pk_bf16_f32 v98, v92, v93
	v_cvt_pk_bf16_f32 v99, v94, v95
	global_store_dwordx4 v59, v[96:99], s[12:13]
	s_cmp_lg_u32 s44, 0
	s_cbranch_scc1 .LBB0_40
	s_cmp_lt_u32 s2, 7680
	s_cbranch_scc0 .Lp0a_lastB
	s_mov_b32 s6, s2
	s_cmp_lt_u32 s6, 1536
	s_cbranch_scc0 .Lp0a_da_1
	s_mul_i32 s20, s6, 683
	s_lshr_b32 s20, s20, 16
	s_mul_i32 s21, s20, 96
	s_sub_u32 s21, s6, s21
	s_lshl_b32 s20, s20, 6
	s_lshl_b32 s21, s21, 5
	s_mul_i32 s23, s20, 3072
	s_add_u32 s23, s23, s21
	s_lshl_b32 s23, s23, 2
	s_add_u32 s8, s30, s23
	s_addc_u32 s9, s31, 0
	s_mov_b32 s10, 12288
	s_mul_i32 s22, s21, 1024
	s_add_u32 s22, s22, s20
	s_lshl_b32 s22, s22, 1
	s_add_u32 s22, s22, 0x100000
	s_add_u32 s12, s42, s22
	s_addc_u32 s13, s43, 0
	s_mov_b32 s14, 2048
	s_branch .Lp0a_da_done

; __device__ __forceinline__ void p0_prologue(KP P, LAS unsigned char* lds, int G) {
;     ...
;     for (int it = gw; it < NITEMS; it += NGW) {
;         int r = it;
;         if (r < 2 * I_AIN) { const int j = r / I_AIN; r -= j * I_AIN; const int kb = r / 96, nb = r % 96;
;             p0_transpose_item(P->attn_w_in + (size_t)j * 1024 * 3072, 3072, 1024, (bf16_t*)(P->ws + WS_WQKV + j * WS_WQKV_STRIDE), 64 * kb, 32 * nb, 32 * nb, scr, lane); continue; }
;         r -= 2 * I_AIN;
;         if (r < 2 * I_AO) { const int j = r / I_AO; r -= j * I_AO; const int kb = r / 32, nb = r % 32;
;             p0_transpose_item(P->attn_w_out + (size_t)j * 1024 * 1024, 1024, 1024, (bf16_t*)(P->ws + WS_WAO + j * WS_WAO_STRIDE), 64 * kb, 32 * nb, 32 * nb, scr, lane); continue; }
;         r -= 2 * I_AO;
;         if (r < 2 * I_GIN) { const int j = r / I_GIN; r -= j * I_GIN; const int kb = r / 96, nb = r % 96; const int n0 = 32 * nb;
;             const int orow = n0 < 1024 ? n0 : (n0 < 2048 ? n0 + 1024 : n0 - 1024);
;             p0_transpose_item(P->gla_w_in + (size_t)j * 1024 * 3088, 3088, 1024, (bf16_t*)(P->ws + WS_WGLA + j * WS_WGLA_STRIDE), 64 * kb, n0, orow, scr, lane); continue; }
;         r -= 2 * I_GIN;
;         if (r < 2 * I_GO) { const int j = r / I_GO; r -= j * I_GO; const int kb = r / 32, nb = r % 32;
;             p0_transpose_item(P->gla_w_out + (size_t)j * 1024 * 1024, 1024, 1024, (bf16_t*)(P->ws + WS_WGO + j * WS_WGO_STRIDE), 64 * kb, 32 * nb, 32 * nb, scr, lane); continue; }
;         r -= 2 * I_GO;
;         if (r < 4 * I_UP) { const int j = r / I_UP; r -= j * I_UP; const int kb = r / 128, nb = r % 128;
;             p0_transpose_item(P->mlp_up + (size_t)j * 1024 * 4096, 4096, 1024, (bf16_t*)(P->ws + WS_WUP + j * WS_WUP_STRIDE), 64 * kb, 32 * nb, 32 * nb, scr, lane); continue; }
;         r -= 4 * I_UP;
;         { const int j = r / I_DN; r -= j * I_DN; const int kb = r / 32, nb = r % 32;
;             p0_transpose_item(P->mlp_dn + (size_t)j * 4096 * 1024, 1024, 4096, (bf16_t*)(P->ws + WS_WDN + j * WS_WDN_STRIDE), 64 * kb, 32 * nb, 32 * nb, scr, lane); }
.Lp0b_entry:
	v_readlane_b32 s2, v254, 58
	s_nop 1
	s_cmp_eq_u32 s2, 1
	s_cbranch_scc0 .LBB0_398
	v_readfirstlane_b32 s3, v194
	s_lshr_b32 s3, s3, 6
	s_sub_u32 s2, s92, 0x80
	s_lshl_b32 s2, s2, 3
	s_add_u32 s2, s2, s3
	s_mul_i32 s3, s3, 0x4400
	s_movk_i32 s81, 0x400
	v_and_b32_e32 v54, 63, v194
	s_load_dwordx2 s[34:35], s[90:91], 0x18
	s_load_dwordx2 s[36:37], s[90:91], 0x30
	s_load_dwordx2 s[38:39], s[90:91], 0x38
	s_load_dwordx2 s[66:67], s[90:91], 0x58
	s_load_dwordx2 s[68:69], s[90:91], 0x68
	s_load_dwordx2 s[70:71], s[90:91], 0x70
	s_load_dwordx2 s[72:73], s[90:91], 0x88
	v_and_b32_e32 v55, 7, v54
	v_lshrrev_b32_e32 v56, 3, v54
	v_mul_u32_u24_e32 v57, 0x410, v55
	v_lshlrev_b32_e32 v58, 4, v55
	v_lshl_add_u32 v57, v56, 2, v57
	v_add_u32_e32 v57, s3, v57
	v_add_u32_e32 v61, 0x2080, v57
	s_mov_b32 s80, 0
	s_waitcnt lgkmcnt(0)
	s_cmp_lt_u32 s2, 16896
	s_cbranch_scc0 .LBB0_398
	s_mov_b32 s19, s2
	s_cmp_lt_u32 s19, 512
	s_cbranch_scc0 .Lp0b_da0_1
	s_lshr_b32 s30, s19, 5
	s_and_b32 s31, s19, 31
	s_lshl_b32 s30, s30, 6
	s_lshl_b32 s31, s31, 5
	s_mul_i32 s33, s30, 1024
	s_add_u32 s33, s33, s31
	s_lshl_b32 s33, s33, 2
	s_add_u32 s4, s66, s33
	s_addc_u32 s5, s67, 0
	s_mov_b32 s6, 4096
	s_mul_i32 s32, s31, 1024
	s_add_u32 s32, s32, s30
	s_lshl_b32 s32, s32, 1
	s_add_u32 s32, s32, 0x1f00000
	s_add_u32 s12, s72, s32
	s_addc_u32 s13, s73, 0
	s_mov_b32 s14, 2048
	s_branch .Lp0b_da0_done
.Lp0b_da0_1:
	s_sub_u32 s19, s19, 512
	s_cmp_lt_u32 s19, 2048
	s_cbranch_scc0 .Lp0b_da0_2
	s_lshr_b32 s30, s19, 7
	s_and_b32 s31, s19, 127
	s_lshl_b32 s30, s30, 6
	s_lshl_b32 s31, s31, 5
	s_mul_i32 s33, s30, 4096
	s_add_u32 s33, s33, s31
	s_lshl_b32 s33, s33, 2
	s_add_u32 s33, s33, 0x1000000
	s_add_u32 s4, s68, s33
	s_addc_u32 s5, s69, 0
	s_mov_b32 s6, 16384
	s_mul_i32 s32, s31, 1024
	s_add_u32 s32, s32, s30
	s_lshl_b32 s32, s32, 1
	s_add_u32 s32, s32, 0x2b00000
	s_add_u32 s12, s72, s32
	s_addc_u32 s13, s73, 0
	s_mov_b32 s14, 2048
	s_branch .Lp0b_da0_done
.Lp0b_da0_2:
	s_sub_u32 s19, s19, 2048
	s_cmp_lt_u32 s19, 2048
	s_cbranch_scc0 .Lp0b_da0_3
	s_lshr_b32 s30, s19, 5
	s_and_b32 s31, s19, 31
	s_lshl_b32 s30, s30, 6
	s_lshl_b32 s31, s31, 5
	s_mul_i32 s33, s30, 1024
	s_add_u32 s33, s33, s31
	s_lshl_b32 s33, s33, 2
	s_add_u32 s33, s33, 0x1000000
	s_add_u32 s4, s70, s33
	s_addc_u32 s5, s71, 0
	s_mov_b32 s6, 4096
	s_mul_i32 s32, s31, 4096
	s_add_u32 s32, s32, s30
	s_lshl_b32 s32, s32, 1
	s_add_u32 s32, s32, 0x4b00000
	s_add_u32 s12, s72, s32
	s_addc_u32 s13, s73, 0
	s_mov_b32 s14, 8192
	s_branch .Lp0b_da0_done
.Lp0b_da0_3:
	s_sub_u32 s19, s19, 2048
	s_cmp_lt_u32 s19, 1536
	s_cbranch_scc0 .Lp0b_da0_4
	s_mul_i32 s30, s19, 683
	s_lshr_b32 s30, s30, 16
	s_mul_i32 s31, s30, 96
	s_sub_u32 s31, s19, s31
	s_lshl_b32 s30, s30, 6
	s_lshl_b32 s31, s31, 5
	s_mul_i32 s33, s30, 3072
	s_add_u32 s33, s33, s31
	s_lshl_b32 s33, s33, 2
	s_add_u32 s33, s33, 0xc00000
	s_add_u32 s4, s34, s33
	s_addc_u32 s5, s35, 0
	s_mov_b32 s6, 12288
	s_mul_i32 s32, s31, 1024
	s_add_u32 s32, s32, s30
	s_lshl_b32 s32, s32, 1
	s_add_u32 s32, s32, 0x700000
	s_add_u32 s12, s72, s32
	s_addc_u32 s13, s73, 0
	s_mov_b32 s14, 2048
	s_branch .Lp0b_da0_done
.Lp0b_da0_4:
	s_sub_u32 s19, s19, 1536
	s_cmp_lt_u32 s19, 512
	s_cbranch_scc0 .Lp0b_da0_5
	s_lshr_b32 s30, s19, 5
	s_and_b32 s31, s19, 31
	s_lshl_b32 s30, s30, 6
	s_lshl_b32 s31, s31, 5
	s_mul_i32 s33, s30, 1024
	s_add_u32 s33, s33, s31
	s_lshl_b32 s33, s33, 2
	s_add_u32 s33, s33, 0x400000
	s_add_u32 s4, s36, s33
	s_addc_u32 s5, s37, 0
	s_mov_b32 s6, 4096
	s_mul_i32 s32, s31, 1024
	s_add_u32 s32, s32, s30
	s_lshl_b32 s32, s32, 1
	s_add_u32 s32, s32, 0xf00000
	s_add_u32 s12, s72, s32
	s_addc_u32 s13, s73, 0
	s_mov_b32 s14, 2048
	s_branch .Lp0b_da0_done
.Lp0b_da0_5:
	s_sub_u32 s19, s19, 512
	s_cmp_lt_u32 s19, 2048
	s_cbranch_scc0 .Lp0b_da0_6
	s_lshr_b32 s30, s19, 7
	s_and_b32 s31, s19, 127
	s_lshl_b32 s30, s30, 6
	s_lshl_b32 s31, s31, 5
	s_mul_i32 s33, s30, 4096
	s_add_u32 s33, s33, s31
	s_lshl_b32 s33, s33, 2
	s_add_u32 s33, s33, 0x2000000
	s_add_u32 s4, s68, s33
	s_addc_u32 s5, s69, 0
	s_mov_b32 s6, 16384
	s_mul_i32 s32, s31, 1024
	s_add_u32 s32, s32, s30
	s_lshl_b32 s32, s32, 1
	s_add_u32 s32, s32, 0x3300000
	s_add_u32 s12, s72, s32
	s_addc_u32 s13, s73, 0
	s_mov_b32 s14, 2048
	s_branch .Lp0b_da0_done
.Lp0b_da0_6:
	s_sub_u32 s19, s19, 2048
	s_cmp_lt_u32 s19, 2048
	s_cbranch_scc0 .Lp0b_da0_7
	s_lshr_b32 s30, s19, 5
	s_and_b32 s31, s19, 31
	s_lshl_b32 s30, s30, 6
	s_lshl_b32 s31, s31, 5
	s_mul_i32 s33, s30, 1024
	s_add_u32 s33, s33, s31
	s_lshl_b32 s33, s33, 2
	s_add_u32 s33, s33, 0x2000000
	s_add_u32 s4, s70, s33
	s_addc_u32 s5, s71, 0
	s_mov_b32 s6, 4096
	s_mul_i32 s32, s31, 4096
	s_add_u32 s32, s32, s30
	s_lshl_b32 s32, s32, 1
	s_add_u32 s32, s32, 0x5300000
	s_add_u32 s12, s72, s32
	s_addc_u32 s13, s73, 0
	s_mov_b32 s14, 8192
	s_branch .Lp0b_da0_done
.Lp0b_da0_7:
	s_sub_u32 s19, s19, 2048
	s_cmp_lt_u32 s19, 1536
	s_cbranch_scc0 .Lp0b_da0_8
	s_mul_i32 s30, s19, 683
	s_lshr_b32 s30, s30, 16
	s_mul_i32 s31, s30, 96
	s_sub_u32 s31, s19, s31
	s_lshl_b32 s30, s30, 6
	s_lshl_b32 s31, s31, 5
	s_mul_i32 s33, s30, 3088
	s_add_u32 s33, s33, s31
	s_lshl_b32 s33, s33, 2
	s_add_u32 s33, s33, 0xc10000
	s_add_u32 s4, s38, s33
	s_addc_u32 s5, s39, 0
	s_mov_b32 s6, 12352
	s_add_u32 s32, s31, 0x400
	s_sub_u32 s33, s31, 0x400
	s_cmp_lt_u32 s31, 0x800
	s_cselect_b32 s32, s32, s33
	s_cmp_lt_u32 s31, 0x400
	s_cselect_b32 s31, s31, s32
	s_mul_i32 s32, s31, 1024
	s_add_u32 s32, s32, s30
	s_lshl_b32 s32, s32, 1
	s_add_u32 s32, s32, 0x1800000
	s_add_u32 s12, s72, s32
	s_addc_u32 s13, s73, 0
	s_mov_b32 s14, 2048
	s_branch .Lp0b_da0_done
; #define LAS __attribute__((address_space(3)))
; __device__ __forceinline__ void p0_transpose_item(const float* W, int ldw, int K, bf16_t* WT, int k0, int n0, int orow0, LAS float* scr, int lane) {
; #pragma unroll 8
; __device__ __forceinline__ void p0_prologue(KP P, LAS unsigned char* lds, int G) {
;     ...
;     for (int it = gw; it < NITEMS; it += NGW) {
;         int r = it;
;         if (r < 2 * I_AIN) { const int j = r / I_AIN; r -= j * I_AIN; const int kb = r / 96, nb = r % 96;
;             p0_transpose_item(P->attn_w_in + (size_t)j * 1024 * 3072, 3072, 1024, (bf16_t*)(P->ws + WS_WQKV + j * WS_WQKV_STRIDE), 64 * kb, 32 * nb, 32 * nb, scr, lane); continue; }
;         r -= 2 * I_AIN;
;         if (r < 2 * I_AO) { const int j = r / I_AO; r -= j * I_AO; const int kb = r / 32, nb = r % 32;
;             p0_transpose_item(P->attn_w_out + (size_t)j * 1024 * 1024, 1024, 1024, (bf16_t*)(P->ws + WS_WAO + j * WS_WAO_STRIDE), 64 * kb, 32 * nb, 32 * nb, scr, lane); continue; }
;         r -= 2 * I_AO;
;         if (r < 2 * I_GIN) { const int j = r / I_GIN; r -= j * I_GIN; const int kb = r / 96, nb = r % 96; const int n0 = 32 * nb;
;             const int orow = n0 < 1024 ? n0 : (n0 < 2048 ? n0 + 1024 : n0 - 1024);
;             p0_transpose_item(P->gla_w_in + (size_t)j * 1024 * 3088, 3088, 1024, (bf16_t*)(P->ws + WS_WGLA + j * WS_WGLA_STRIDE), 64 * kb, n0, orow, scr, lane); continue; }
;         r -= 2 * I_GIN;
;         if (r < 2 * I_GO) { const int j = r / I_GO; r -= j * I_GO; const int kb = r / 32, nb = r % 32;
;             p0_transpose_item(P->gla_w_out + (size_t)j * 1024 * 1024, 1024, 1024, (bf16_t*)(P->ws + WS_WGO + j * WS_WGO_STRIDE), 64 * kb, 32 * nb, 32 * nb, scr, lane); continue; }
;         r -= 2 * I_GO;
;         if (r < 4 * I_UP) { const int j = r / I_UP; r -= j * I_UP; const int kb = r / 128, nb = r % 128;
;             p0_transpose_item(P->mlp_up + (size_t)j * 1024 * 4096, 4096, 1024, (bf16_t*)(P->ws + WS_WUP + j * WS_WUP_STRIDE), 64 * kb, 32 * nb, 32 * nb, scr, lane); continue; }
;         r -= 4 * I_UP;
;         { const int j = r / I_DN; r -= j * I_DN; const int kb = r / 32, nb = r % 32;
;             p0_transpose_item(P->mlp_dn + (size_t)j * 4096 * 1024, 1024, 4096, (bf16_t*)(P->ws + WS_WDN + j * WS_WDN_STRIDE), 64 * kb, 32 * nb, 32 * nb, scr, lane); }
.Lp0b_da0_8:
	s_sub_u32 s19, s19, 1536
	s_cmp_lt_u32 s19, 512
	s_cbranch_scc0 .Lp0b_da0_9
	s_lshr_b32 s30, s19, 5
	s_and_b32 s31, s19, 31
	s_lshl_b32 s30, s30, 6
	s_lshl_b32 s31, s31, 5
	s_mul_i32 s33, s30, 1024
	s_add_u32 s33, s33, s31
	s_lshl_b32 s33, s33, 2
	s_add_u32 s33, s33, 0x400000
	s_add_u32 s4, s66, s33
	s_addc_u32 s5, s67, 0
	s_mov_b32 s6, 4096
	s_mul_i32 s32, s31, 1024
	s_add_u32 s32, s32, s30
	s_lshl_b32 s32, s32, 1
	s_add_u32 s32, s32, 0x2100000
	s_add_u32 s12, s72, s32
	s_addc_u32 s13, s73, 0
	s_mov_b32 s14, 2048
	s_branch .Lp0b_da0_done
.Lp0b_da0_9:
	s_sub_u32 s19, s19, 512
	s_cmp_lt_u32 s19, 2048
	s_cbranch_scc0 .Lp0b_da0_10
	s_lshr_b32 s30, s19, 7
	s_and_b32 s31, s19, 127
	s_lshl_b32 s30, s30, 6
	s_lshl_b32 s31, s31, 5
	s_mul_i32 s33, s30, 4096
	s_add_u32 s33, s33, s31
	s_lshl_b32 s33, s33, 2
	s_add_u32 s33, s33, 0x3000000
	s_add_u32 s4, s68, s33
	s_addc_u32 s5, s69, 0
	s_mov_b32 s6, 16384
	s_mul_i32 s32, s31, 1024
	s_add_u32 s32, s32, s30
	s_lshl_b32 s32, s32, 1
	s_add_u32 s32, s32, 0x3b00000
	s_add_u32 s12, s72, s32
	s_addc_u32 s13, s73, 0
	s_mov_b32 s14, 2048
	s_branch .Lp0b_da0_done
.Lp0b_da0_10:
	s_sub_u32 s19, s19, 2048
	s_lshr_b32 s30, s19, 5
	s_and_b32 s31, s19, 31
	s_lshl_b32 s30, s30, 6
	s_lshl_b32 s31, s31, 5
	s_mul_i32 s33, s30, 1024
	s_add_u32 s33, s33, s31
	s_lshl_b32 s33, s33, 2
	s_add_u32 s33, s33, 0x3000000
	s_add_u32 s4, s70, s33
	s_addc_u32 s5, s71, 0
	s_mov_b32 s6, 4096
	s_mul_i32 s32, s31, 4096
	s_add_u32 s32, s32, s30
	s_lshl_b32 s32, s32, 1
	s_add_u32 s32, s32, 0x5b00000
	s_add_u32 s12, s72, s32
	s_addc_u32 s13, s73, 0
	s_mov_b32 s14, 8192
.Lp0b_da0_done:
	v_mad_u32_u24 v60, v56, s6, v58
	s_lshl_b32 s8, s6, 3
	s_add_i32 s9, s3, 0
	s_mov_b32 m0, s9
	s_add_i32 s9, s9, 1040
	global_load_lds_dwordx4 v60, s[4:5]
	s_add_u32 s4, s4, s8
	s_addc_u32 s5, s5, 0
	s_mov_b32 m0, s9
	s_add_i32 s9, s9, 1040
	global_load_lds_dwordx4 v60, s[4:5]
	s_add_u32 s4, s4, s8
	s_addc_u32 s5, s5, 0
	s_mov_b32 m0, s9
	s_add_i32 s9, s9, 1040
	global_load_lds_dwordx4 v60, s[4:5]
	s_add_u32 s4, s4, s8
	s_addc_u32 s5, s5, 0
	s_mov_b32 m0, s9
	s_add_i32 s9, s9, 1040
	global_load_lds_dwordx4 v60, s[4:5]
	s_add_u32 s4, s4, s8
	s_addc_u32 s5, s5, 0
	s_mov_b32 m0, s9
	s_add_i32 s9, s9, 1040
	global_load_lds_dwordx4 v60, s[4:5]
	s_add_u32 s4, s4, s8
	s_addc_u32 s5, s5, 0
	s_mov_b32 m0, s9
	s_add_i32 s9, s9, 1040
	global_load_lds_dwordx4 v60, s[4:5]
	s_add_u32 s4, s4, s8
	s_addc_u32 s5, s5, 0
	s_mov_b32 m0, s9
	s_add_i32 s9, s9, 1040
	global_load_lds_dwordx4 v60, s[4:5]
	s_add_u32 s4, s4, s8
	s_addc_u32 s5, s5, 0
	s_mov_b32 m0, s9
	s_add_i32 s9, s9, 1040
	global_load_lds_dwordx4 v60, s[4:5]
	s_add_i32 s2, s2, s81
.Lp0b_loop:
	s_cmp_lt_u32 s2, 16896
	s_cbranch_scc0 .Lp0b_lastA
	s_mov_b32 s19, s2
	s_cmp_lt_u32 s19, 512
	s_cbranch_scc0 .Lp0b_db_1
	s_lshr_b32 s30, s19, 5
	s_and_b32 s31, s19, 31
	s_lshl_b32 s30, s30, 6
	s_lshl_b32 s31, s31, 5
	s_mul_i32 s33, s30, 1024
	s_add_u32 s33, s33, s31
	s_lshl_b32 s33, s33, 2
	s_add_u32 s4, s66, s33
	s_addc_u32 s5, s67, 0
	s_mov_b32 s6, 4096
	s_mul_i32 s32, s31, 1024
	s_add_u32 s32, s32, s30
	s_lshl_b32 s32, s32, 1
	s_add_u32 s32, s32, 0x1f00000
	s_add_u32 s16, s72, s32
	s_addc_u32 s17, s73, 0
	s_mov_b32 s15, 2048
	s_branch .Lp0b_db_done
.Lp0b_db_1:
	s_sub_u32 s19, s19, 512
	s_cmp_lt_u32 s19, 2048
	s_cbranch_scc0 .Lp0b_db_2
	s_lshr_b32 s30, s19, 7
	s_and_b32 s31, s19, 127
	s_lshl_b32 s30, s30, 6
	s_lshl_b32 s31, s31, 5
	s_mul_i32 s33, s30, 4096
	s_add_u32 s33, s33, s31
	s_lshl_b32 s33, s33, 2
	s_add_u32 s33, s33, 0x1000000
	s_add_u32 s4, s68, s33
	s_addc_u32 s5, s69, 0
	s_mov_b32 s6, 16384
	s_mul_i32 s32, s31, 1024
	s_add_u32 s32, s32, s30
	s_lshl_b32 s32, s32, 1
	s_add_u32 s32, s32, 0x2b00000
	s_add_u32 s16, s72, s32
	s_addc_u32 s17, s73, 0
	s_mov_b32 s15, 2048
	s_branch .Lp0b_db_done
.Lp0b_db_2:
	s_sub_u32 s19, s19, 2048
	s_cmp_lt_u32 s19, 2048
	s_cbranch_scc0 .Lp0b_db_3
	s_lshr_b32 s30, s19, 5
	s_and_b32 s31, s19, 31
	s_lshl_b32 s30, s30, 6
	s_lshl_b32 s31, s31, 5
	s_mul_i32 s33, s30, 1024
	s_add_u32 s33, s33, s31
	s_lshl_b32 s33, s33, 2
	s_add_u32 s33, s33, 0x1000000
	s_add_u32 s4, s70, s33
	s_addc_u32 s5, s71, 0
	s_mov_b32 s6, 4096
	s_mul_i32 s32, s31, 4096
	s_add_u32 s32, s32, s30
	s_lshl_b32 s32, s32, 1
	s_add_u32 s32, s32, 0x4b00000
	s_add_u32 s16, s72, s32
	s_addc_u32 s17, s73, 0
	s_mov_b32 s15, 8192
	s_branch .Lp0b_db_done
.Lp0b_db_3:
	s_sub_u32 s19, s19, 2048
	s_cmp_lt_u32 s19, 1536
	s_cbranch_scc0 .Lp0b_db_4
	s_mul_i32 s30, s19, 683
	s_lshr_b32 s30, s30, 16
	s_mul_i32 s31, s30, 96
	s_sub_u32 s31, s19, s31
	s_lshl_b32 s30, s30, 6
	s_lshl_b32 s31, s31, 5
	s_mul_i32 s33, s30, 3072
	s_add_u32 s33, s33, s31
	s_lshl_b32 s33, s33, 2
	s_add_u32 s33, s33, 0xc00000
	s_add_u32 s4, s34, s33
	s_addc_u32 s5, s35, 0
	s_mov_b32 s6, 12288
	s_mul_i32 s32, s31, 1024
	s_add_u32 s32, s32, s30
	s_lshl_b32 s32, s32, 1
	s_add_u32 s32, s32, 0x700000
	s_add_u32 s16, s72, s32
	s_addc_u32 s17, s73, 0
	s_mov_b32 s15, 2048
	s_branch .Lp0b_db_done
.Lp0b_db_4:
	s_sub_u32 s19, s19, 1536
	s_cmp_lt_u32 s19, 512
	s_cbranch_scc0 .Lp0b_db_5
	s_lshr_b32 s30, s19, 5
	s_and_b32 s31, s19, 31
	s_lshl_b32 s30, s30, 6
	s_lshl_b32 s31, s31, 5
	s_mul_i32 s33, s30, 1024
	s_add_u32 s33, s33, s31
	s_lshl_b32 s33, s33, 2
	s_add_u32 s33, s33, 0x400000
	s_add_u32 s4, s36, s33
	s_addc_u32 s5, s37, 0
	s_mov_b32 s6, 4096
	s_mul_i32 s32, s31, 1024
	s_add_u32 s32, s32, s30
	s_lshl_b32 s32, s32, 1
	s_add_u32 s32, s32, 0xf00000
	s_add_u32 s16, s72, s32
	s_addc_u32 s17, s73, 0
	s_mov_b32 s15, 2048
	s_branch .Lp0b_db_done
; __device__ __forceinline__ void p0_transpose_item(const float* W, int ldw, int K, bf16_t* WT, int k0, int n0, int orow0, LAS float* scr, int lane) {
;     ...
;     const int c = lane & 7;
; #pragma unroll
;     for (int j = 0; j < 4; ++j) { const int n = (lane >> 3) + 8 * j; const LAS float* s = scr + (8 * c) * 33 + n;
; __device__ __forceinline__ void p0_prologue(KP P, LAS unsigned char* lds, int G) {
;     ...
;     for (int it = gw; it < NITEMS; it += NGW) {
;         int r = it;
;         if (r < 2 * I_AIN) { const int j = r / I_AIN; r -= j * I_AIN; const int kb = r / 96, nb = r % 96;
;             p0_transpose_item(P->attn_w_in + (size_t)j * 1024 * 3072, 3072, 1024, (bf16_t*)(P->ws + WS_WQKV + j * WS_WQKV_STRIDE), 64 * kb, 32 * nb, 32 * nb, scr, lane); continue; }
;         r -= 2 * I_AIN;
;         if (r < 2 * I_AO) { const int j = r / I_AO; r -= j * I_AO; const int kb = r / 32, nb = r % 32;
;             p0_transpose_item(P->attn_w_out + (size_t)j * 1024 * 1024, 1024, 1024, (bf16_t*)(P->ws + WS_WAO + j * WS_WAO_STRIDE), 64 * kb, 32 * nb, 32 * nb, scr, lane); continue; }
;         r -= 2 * I_AO;
;         if (r < 2 * I_GIN) { const int j = r / I_GIN; r -= j * I_GIN; const int kb = r / 96, nb = r % 96; const int n0 = 32 * nb;
;             const int orow = n0 < 1024 ? n0 : (n0 < 2048 ? n0 + 1024 : n0 - 1024);
;             p0_transpose_item(P->gla_w_in + (size_t)j * 1024 * 3088, 3088, 1024, (bf16_t*)(P->ws + WS_WGLA + j * WS_WGLA_STRIDE), 64 * kb, n0, orow, scr, lane); continue; }
;         r -= 2 * I_GIN;
;         if (r < 2 * I_GO) { const int j = r / I_GO; r -= j * I_GO; const int kb = r / 32, nb = r % 32;
;             p0_transpose_item(P->gla_w_out + (size_t)j * 1024 * 1024, 1024, 1024, (bf16_t*)(P->ws + WS_WGO + j * WS_WGO_STRIDE), 64 * kb, 32 * nb, 32 * nb, scr, lane); continue; }
;         r -= 2 * I_GO;
;         if (r < 4 * I_UP) { const int j = r / I_UP; r -= j * I_UP; const int kb = r / 128, nb = r % 128;
;             p0_transpose_item(P->mlp_up + (size_t)j * 1024 * 4096, 4096, 1024, (bf16_t*)(P->ws + WS_WUP + j * WS_WUP_STRIDE), 64 * kb, 32 * nb, 32 * nb, scr, lane); continue; }
;         r -= 4 * I_UP;
;         { const int j = r / I_DN; r -= j * I_DN; const int kb = r / 32, nb = r % 32;
;             p0_transpose_item(P->mlp_dn + (size_t)j * 4096 * 1024, 1024, 4096, (bf16_t*)(P->ws + WS_WDN + j * WS_WDN_STRIDE), 64 * kb, 32 * nb, 32 * nb, scr, lane); }
.Lp0b_db_5:
	s_sub_u32 s19, s19, 512
	s_cmp_lt_u32 s19, 2048
	s_cbranch_scc0 .Lp0b_db_6
	s_lshr_b32 s30, s19, 7
	s_and_b32 s31, s19, 127
	s_lshl_b32 s30, s30, 6
	s_lshl_b32 s31, s31, 5
	s_mul_i32 s33, s30, 4096
	s_add_u32 s33, s33, s31
	s_lshl_b32 s33, s33, 2
	s_add_u32 s33, s33, 0x2000000
	s_add_u32 s4, s68, s33
	s_addc_u32 s5, s69, 0
	s_mov_b32 s6, 16384
	s_mul_i32 s32, s31, 1024
	s_add_u32 s32, s32, s30
	s_lshl_b32 s32, s32, 1
	s_add_u32 s32, s32, 0x3300000
	s_add_u32 s16, s72, s32
	s_addc_u32 s17, s73, 0
	s_mov_b32 s15, 2048
	s_branch .Lp0b_db_done
.Lp0b_db_6:
	s_sub_u32 s19, s19, 2048
	s_cmp_lt_u32 s19, 2048
	s_cbranch_scc0 .Lp0b_db_7
	s_lshr_b32 s30, s19, 5
	s_and_b32 s31, s19, 31
	s_lshl_b32 s30, s30, 6
	s_lshl_b32 s31, s31, 5
	s_mul_i32 s33, s30, 1024
	s_add_u32 s33, s33, s31
	s_lshl_b32 s33, s33, 2
	s_add_u32 s33, s33, 0x2000000
	s_add_u32 s4, s70, s33
	s_addc_u32 s5, s71, 0
	s_mov_b32 s6, 4096
	s_mul_i32 s32, s31, 4096
	s_add_u32 s32, s32, s30
	s_lshl_b32 s32, s32, 1
	s_add_u32 s32, s32, 0x5300000
	s_add_u32 s16, s72, s32
	s_addc_u32 s17, s73, 0
	s_mov_b32 s15, 8192
	s_branch .Lp0b_db_done
.Lp0b_db_7:
	s_sub_u32 s19, s19, 2048
	s_cmp_lt_u32 s19, 1536
	s_cbranch_scc0 .Lp0b_db_8
	s_mul_i32 s30, s19, 683
	s_lshr_b32 s30, s30, 16
	s_mul_i32 s31, s30, 96
	s_sub_u32 s31, s19, s31
	s_lshl_b32 s30, s30, 6
	s_lshl_b32 s31, s31, 5
	s_mul_i32 s33, s30, 3088
	s_add_u32 s33, s33, s31
	s_lshl_b32 s33, s33, 2
	s_add_u32 s33, s33, 0xc10000
	s_add_u32 s4, s38, s33
	s_addc_u32 s5, s39, 0
	s_mov_b32 s6, 12352
	s_add_u32 s32, s31, 0x400
	s_sub_u32 s33, s31, 0x400
	s_cmp_lt_u32 s31, 0x800
	s_cselect_b32 s32, s32, s33
	s_cmp_lt_u32 s31, 0x400
	s_cselect_b32 s31, s31, s32
	s_mul_i32 s32, s31, 1024
	s_add_u32 s32, s32, s30
	s_lshl_b32 s32, s32, 1
	s_add_u32 s32, s32, 0x1800000
	s_add_u32 s16, s72, s32
	s_addc_u32 s17, s73, 0
	s_mov_b32 s15, 2048
	s_branch .Lp0b_db_done
.Lp0b_db_8:
	s_sub_u32 s19, s19, 1536
	s_cmp_lt_u32 s19, 512
	s_cbranch_scc0 .Lp0b_db_9
	s_lshr_b32 s30, s19, 5
	s_and_b32 s31, s19, 31
	s_lshl_b32 s30, s30, 6
	s_lshl_b32 s31, s31, 5
	s_mul_i32 s33, s30, 1024
	s_add_u32 s33, s33, s31
	s_lshl_b32 s33, s33, 2
	s_add_u32 s33, s33, 0x400000
	s_add_u32 s4, s66, s33
	s_addc_u32 s5, s67, 0
	s_mov_b32 s6, 4096
	s_mul_i32 s32, s31, 1024
	s_add_u32 s32, s32, s30
	s_lshl_b32 s32, s32, 1
	s_add_u32 s32, s32, 0x2100000
	s_add_u32 s16, s72, s32
	s_addc_u32 s17, s73, 0
	s_mov_b32 s15, 2048
	s_branch .Lp0b_db_done
.Lp0b_db_9:
	s_sub_u32 s19, s19, 512
	s_cmp_lt_u32 s19, 2048
	s_cbranch_scc0 .Lp0b_db_10
	s_lshr_b32 s30, s19, 7
	s_and_b32 s31, s19, 127
	s_lshl_b32 s30, s30, 6
	s_lshl_b32 s31, s31, 5
	s_mul_i32 s33, s30, 4096
	s_add_u32 s33, s33, s31
	s_lshl_b32 s33, s33, 2
	s_add_u32 s33, s33, 0x3000000
	s_add_u32 s4, s68, s33
	s_addc_u32 s5, s69, 0
	s_mov_b32 s6, 16384
	s_mul_i32 s32, s31, 1024
	s_add_u32 s32, s32, s30
	s_lshl_b32 s32, s32, 1
	s_add_u32 s32, s32, 0x3b00000
	s_add_u32 s16, s72, s32
	s_addc_u32 s17, s73, 0
	s_mov_b32 s15, 2048
	s_branch .Lp0b_db_done
.Lp0b_db_10:
	s_sub_u32 s19, s19, 2048
	s_lshr_b32 s30, s19, 5
	s_and_b32 s31, s19, 31
	s_lshl_b32 s30, s30, 6
	s_lshl_b32 s31, s31, 5
	s_mul_i32 s33, s30, 1024
	s_add_u32 s33, s33, s31
	s_lshl_b32 s33, s33, 2
	s_add_u32 s33, s33, 0x3000000
	s_add_u32 s4, s70, s33
	s_addc_u32 s5, s71, 0
	s_mov_b32 s6, 4096
	s_mul_i32 s32, s31, 4096
	s_add_u32 s32, s32, s30
	s_lshl_b32 s32, s32, 1
	s_add_u32 s32, s32, 0x5b00000
	s_add_u32 s16, s72, s32
	s_addc_u32 s17, s73, 0
	s_mov_b32 s15, 8192
.Lp0b_db_done:
	v_mad_u32_u24 v60, v56, s6, v58
	s_lshl_b32 s8, s6, 3
	s_add_i32 s9, s3, 8320
	s_mov_b32 m0, s9
	s_add_i32 s9, s9, 1040
	global_load_lds_dwordx4 v60, s[4:5]
	s_add_u32 s4, s4, s8
	s_addc_u32 s5, s5, 0
	s_mov_b32 m0, s9
	s_add_i32 s9, s9, 1040
	global_load_lds_dwordx4 v60, s[4:5]
	s_add_u32 s4, s4, s8
	s_addc_u32 s5, s5, 0
	s_mov_b32 m0, s9
	s_add_i32 s9, s9, 1040
	global_load_lds_dwordx4 v60, s[4:5]
	s_add_u32 s4, s4, s8
	s_addc_u32 s5, s5, 0
	s_mov_b32 m0, s9
	s_add_i32 s9, s9, 1040
	global_load_lds_dwordx4 v60, s[4:5]
	s_add_u32 s4, s4, s8
	s_addc_u32 s5, s5, 0
	s_mov_b32 m0, s9
	s_add_i32 s9, s9, 1040
	global_load_lds_dwordx4 v60, s[4:5]
	s_add_u32 s4, s4, s8
	s_addc_u32 s5, s5, 0
	s_mov_b32 m0, s9
	s_add_i32 s9, s9, 1040
	global_load_lds_dwordx4 v60, s[4:5]
	s_add_u32 s4, s4, s8
	s_addc_u32 s5, s5, 0
	s_mov_b32 m0, s9
	s_add_i32 s9, s9, 1040
	global_load_lds_dwordx4 v60, s[4:5]
	s_add_u32 s4, s4, s8
	s_addc_u32 s5, s5, 0
	s_mov_b32 m0, s9
	s_add_i32 s9, s9, 1040
	global_load_lds_dwordx4 v60, s[4:5]
	s_add_i32 s2, s2, s81
	s_waitcnt vmcnt(8)
.Lp0b_consA:
	ds_read2_b32 v[64:65], v57 offset0:0 offset1:32
	ds_read2_b32 v[66:67], v57 offset0:64 offset1:96
	ds_read2_b32 v[68:69], v57 offset0:128 offset1:160
	ds_read2_b32 v[70:71], v57 offset0:192 offset1:224
	ds_read2_b32 v[72:73], v57 offset0:8 offset1:40
	ds_read2_b32 v[74:75], v57 offset0:72 offset1:104
	ds_read2_b32 v[76:77], v57 offset0:136 offset1:168
	ds_read2_b32 v[78:79], v57 offset0:200 offset1:232
	ds_read2_b32 v[80:81], v57 offset0:16 offset1:48
	ds_read2_b32 v[82:83], v57 offset0:80 offset1:112
	ds_read2_b32 v[84:85], v57 offset0:144 offset1:176
	ds_read2_b32 v[86:87], v57 offset0:208 offset1:240
	ds_read2_b32 v[88:89], v57 offset0:24 offset1:56
	ds_read2_b32 v[90:91], v57 offset0:88 offset1:120
	ds_read2_b32 v[92:93], v57 offset0:152 offset1:184
	ds_read2_b32 v[94:95], v57 offset0:216 offset1:248
	s_waitcnt lgkmcnt(0)
	v_mad_u32_u24 v59, v56, s14, v58
	s_lshl_b32 s19, s14, 3
	v_cvt_pk_bf16_f32 v96, v64, v65
	v_cvt_pk_bf16_f32 v97, v66, v67
	v_cvt_pk_bf16_f32 v98, v68, v69
	v_cvt_pk_bf16_f32 v99, v70, v71
	global_store_dwordx4 v59, v[96:99], s[12:13]
	s_add_u32 s12, s12, s19
	s_addc_u32 s13, s13, 0
	s_nop 0
	v_cvt_pk_bf16_f32 v96, v72, v73
	v_cvt_pk_bf16_f32 v97, v74, v75
	v_cvt_pk_bf16_f32 v98, v76, v77
	v_cvt_pk_bf16_f32 v99, v78, v79
	global_store_dwordx4 v59, v[96:99], s[12:13]
	s_add_u32 s12, s12, s19
	s_addc_u32 s13, s13, 0
	s_nop 0
	v_cvt_pk_bf16_f32 v96, v80, v81
	v_cvt_pk_bf16_f32 v97, v82, v83
	v_cvt_pk_bf16_f32 v98, v84, v85
	v_cvt_pk_bf16_f32 v99, v86, v87
	global_store_dwordx4 v59, v[96:99], s[12:13]
	s_add_u32 s12, s12, s19
	s_addc_u32 s13, s13, 0
	s_nop 0
	v_cvt_pk_bf16_f32 v96, v88, v89
	v_cvt_pk_bf16_f32 v97, v90, v91
	v_cvt_pk_bf16_f32 v98, v92, v93
	v_cvt_pk_bf16_f32 v99, v94, v95
	global_store_dwordx4 v59, v[96:99], s[12:13]
	s_cmp_lg_u32 s80, 0
	s_cbranch_scc1 .LBB0_398
	s_cmp_lt_u32 s2, 16896
	s_cbranch_scc0 .Lp0b_lastB
	s_mov_b32 s19, s2
	s_cmp_lt_u32 s19, 512
	s_cbranch_scc0 .Lp0b_da_1
	s_lshr_b32 s30, s19, 5
	s_and_b32 s31, s19, 31
	s_lshl_b32 s30, s30, 6
	s_lshl_b32 s31, s31, 5
	s_mul_i32 s33, s30, 1024
	s_add_u32 s33, s33, s31
	s_lshl_b32 s33, s33, 2
	s_add_u32 s4, s66, s33
	s_addc_u32 s5, s67, 0
	s_mov_b32 s6, 4096
	s_mul_i32 s32, s31, 1024
	s_add_u32 s32, s32, s30
	s_lshl_b32 s32, s32, 1
	s_add_u32 s32, s32, 0x1f00000
	s_add_u32 s12, s72, s32
	s_addc_u32 s13, s73, 0
	s_mov_b32 s14, 2048
	s_branch .Lp0b_da_done

; #define LAS __attribute__((address_space(3)))
; __device__ __forceinline__ unsigned pk_bf16(float lo, float hi) { f32x2_t v = {lo, hi}; bf16x2_t b = __builtin_convertvector(v, bf16x2_t); return __builtin_bit_cast(unsigned, b); }
; __device__ __forceinline__ void p0_transpose_item(const float* W, int ldw, int K, bf16_t* WT, int k0, int n0, int orow0, LAS float* scr, int lane) {
; #pragma unroll 8
;     for (int i = 0; i < 32; ++i) { const int kk = 2 * i + (lane >> 5); scr[kk * 33 + (lane & 31)] = W[(size_t)(k0 + kk) * ldw + n0 + (lane & 31)]; }
;     asm volatile("s_waitcnt lgkmcnt(0)" ::: "memory");
;     const int c = lane & 7;
; #pragma unroll
;     for (int j = 0; j < 4; ++j) { const int n = (lane >> 3) + 8 * j; const LAS float* s = scr + (8 * c) * 33 + n;
;         u32x4 o; o.x = pk_bf16(s[0 * 33], s[1 * 33]); o.y = pk_bf16(s[2 * 33], s[3 * 33]); o.z = pk_bf16(s[4 * 33], s[5 * 33]); o.w = pk_bf16(s[6 * 33], s[7 * 33]);
;         *(u32x4*)(WT + (size_t)(orow0 + n) * K + k0 + 8 * c) = o; }
;     asm volatile("s_waitcnt lgkmcnt(0)" ::: "memory");
.Lp0b_da_done:
	v_mad_u32_u24 v60, v56, s6, v58
	s_lshl_b32 s8, s6, 3
	s_add_i32 s9, s3, 0
	s_mov_b32 m0, s9
	s_add_i32 s9, s9, 1040
	global_load_lds_dwordx4 v60, s[4:5]
	s_add_u32 s4, s4, s8
	s_addc_u32 s5, s5, 0
	s_mov_b32 m0, s9
	s_add_i32 s9, s9, 1040
	global_load_lds_dwordx4 v60, s[4:5]
	s_add_u32 s4, s4, s8
	s_addc_u32 s5, s5, 0
	s_mov_b32 m0, s9
	s_add_i32 s9, s9, 1040
	global_load_lds_dwordx4 v60, s[4:5]
	s_add_u32 s4, s4, s8
	s_addc_u32 s5, s5, 0
	s_mov_b32 m0, s9
	s_add_i32 s9, s9, 1040
	global_load_lds_dwordx4 v60, s[4:5]
	s_add_u32 s4, s4, s8
	s_addc_u32 s5, s5, 0
	s_mov_b32 m0, s9
	s_add_i32 s9, s9, 1040
	global_load_lds_dwordx4 v60, s[4:5]
	s_add_u32 s4, s4, s8
	s_addc_u32 s5, s5, 0
	s_mov_b32 m0, s9
	s_add_i32 s9, s9, 1040
	global_load_lds_dwordx4 v60, s[4:5]
	s_add_u32 s4, s4, s8
	s_addc_u32 s5, s5, 0
	s_mov_b32 m0, s9
	s_add_i32 s9, s9, 1040
	global_load_lds_dwordx4 v60, s[4:5]
	s_add_u32 s4, s4, s8
	s_addc_u32 s5, s5, 0
	s_mov_b32 m0, s9
	s_add_i32 s9, s9, 1040
	global_load_lds_dwordx4 v60, s[4:5]
	s_add_i32 s2, s2, s81
	s_waitcnt vmcnt(8)
.Lp0b_consB:
	ds_read2_b32 v[64:65], v61 offset0:0 offset1:32
	ds_read2_b32 v[66:67], v61 offset0:64 offset1:96
	ds_read2_b32 v[68:69], v61 offset0:128 offset1:160
	ds_read2_b32 v[70:71], v61 offset0:192 offset1:224
	ds_read2_b32 v[72:73], v61 offset0:8 offset1:40
	ds_read2_b32 v[74:75], v61 offset0:72 offset1:104
	ds_read2_b32 v[76:77], v61 offset0:136 offset1:168
	ds_read2_b32 v[78:79], v61 offset0:200 offset1:232
	ds_read2_b32 v[80:81], v61 offset0:16 offset1:48
	ds_read2_b32 v[82:83], v61 offset0:80 offset1:112
	ds_read2_b32 v[84:85], v61 offset0:144 offset1:176
	ds_read2_b32 v[86:87], v61 offset0:208 offset1:240
	ds_read2_b32 v[88:89], v61 offset0:24 offset1:56
	ds_read2_b32 v[90:91], v61 offset0:88 offset1:120
	ds_read2_b32 v[92:93], v61 offset0:152 offset1:184
	ds_read2_b32 v[94:95], v61 offset0:216 offset1:248
	s_waitcnt lgkmcnt(0)
	v_mad_u32_u24 v59, v56, s15, v58
	s_lshl_b32 s19, s15, 3
	v_cvt_pk_bf16_f32 v96, v64, v65
	v_cvt_pk_bf16_f32 v97, v66, v67
	v_cvt_pk_bf16_f32 v98, v68, v69
	v_cvt_pk_bf16_f32 v99, v70, v71
	global_store_dwordx4 v59, v[96:99], s[16:17]
	s_add_u32 s16, s16, s19
	s_addc_u32 s17, s17, 0
	s_nop 0
	v_cvt_pk_bf16_f32 v96, v72, v73
	v_cvt_pk_bf16_f32 v97, v74, v75
	v_cvt_pk_bf16_f32 v98, v76, v77
	v_cvt_pk_bf16_f32 v99, v78, v79
	global_store_dwordx4 v59, v[96:99], s[16:17]
	s_add_u32 s16, s16, s19
	s_addc_u32 s17, s17, 0
	s_nop 0
	v_cvt_pk_bf16_f32 v96, v80, v81
	v_cvt_pk_bf16_f32 v97, v82, v83
	v_cvt_pk_bf16_f32 v98, v84, v85
	v_cvt_pk_bf16_f32 v99, v86, v87
	global_store_dwordx4 v59, v[96:99], s[16:17]
	s_add_u32 s16, s16, s19
	s_addc_u32 s17, s17, 0
	s_nop 0
	v_cvt_pk_bf16_f32 v96, v88, v89
	v_cvt_pk_bf16_f32 v97, v90, v91
	v_cvt_pk_bf16_f32 v98, v92, v93
	v_cvt_pk_bf16_f32 v99, v94, v95
	global_store_dwordx4 v59, v[96:99], s[16:17]
	s_cmp_lg_u32 s80, 0
	s_cbranch_scc1 .LBB0_398
	s_branch .Lp0b_loop
.Lp0b_lastA:
	s_mov_b32 s80, 1
	s_waitcnt vmcnt(0)
	s_branch .Lp0b_consA
.Lp0b_lastB:
	s_mov_b32 s80, 1
	s_waitcnt vmcnt(0)
	s_branch .Lp0b_consB
	s_branch .LBB0_398
